# hand-written phase-1 K-loop (scalar-base LDS-DMA, both k-halves fetched up front) + vectorised LoRA-input loop in phase 2
# speedup vs baseline: 1.0077x; 1.0077x over previous
.LBB0_121:
	s_and_b64 vcc, exec, s[6:7]
	s_lshl_b32 s45, s8, 12
	s_add_u32 s36, s94, s45
	s_addc_u32 s37, s95, 0
	s_add_u32 s36, s36, 0x15000000
	s_addc_u32 s37, s37, 0
	s_lshl_b32 s45, s81, 12
	s_add_u32 s40, s94, s45
	s_addc_u32 s41, s95, 0
	s_add_u32 s40, s40, 0x19000000
	s_addc_u32 s41, s41, 0
	s_cbranch_vccz .Lp1_notfirst
	v_lshrrev_b32_e32 v203, 3, v199
	v_lshrrev_b32_e32 v204, 4, v199
	v_xor_b32_e32 v204, v204, v199
	v_and_b32_e32 v204, 7, v204
	v_lshlrev_b32_e32 v204, 4, v204
	v_lshl_add_u32 v194, v203, 12, v204
	v_add_u32_e32 v195, 0x20000, v194
	v_add_u32_e32 v196, 0x40000, v194
	v_add_u32_e32 v197, 0x60000, v194
	v_and_b32_e32 v203, 15, v199
	v_bfe_u32 v204, v199, 4, 2
	v_lshrrev_b32_e32 v205, 1, v203
	v_xor_b32_e32 v204, v204, v205
	v_lshlrev_b32_e32 v204, 4, v204
	v_xor_b32_e32 v205, 64, v204
	v_lshrrev_b32_e32 v198, 7, v199
	v_lshl_add_u32 v198, v198, 6, v203
	v_lshlrev_b32_e32 v198, 7, v198
	v_bfe_u32 v201, v199, 6, 1
	v_lshl_add_u32 v201, v201, 6, v203
	v_lshlrev_b32_e32 v201, 7, v201
	v_add_u32_e32 v201, 0x8000, v201
	v_add_u32_e32 v200, v198, v205
	v_add_u32_e32 v202, v201, v205
	v_add_u32_e32 v198, v198, v204
	v_add_u32_e32 v201, v201, v204
	v_lshrrev_b32_e32 v203, 6, v199
	v_lshlrev_b32_e32 v203, 10, v203
	s_nop 0
	v_readfirstlane_b32 s32, v203
	s_barrier
	s_add_u32 m0, s32, 0x0
	s_nop 0
	global_load_lds_dwordx4 v194, s[36:37]
	s_add_u32 m0, s32, 0x8000
	s_nop 0
	global_load_lds_dwordx4 v194, s[40:41]
	s_add_u32 m0, s32, 0x1000
	s_nop 0
	global_load_lds_dwordx4 v195, s[36:37]
	s_add_u32 m0, s32, 0x9000
	s_nop 0
	global_load_lds_dwordx4 v195, s[40:41]
	s_add_u32 m0, s32, 0x2000
	s_nop 0
	global_load_lds_dwordx4 v196, s[36:37]
	s_add_u32 m0, s32, 0xa000
	s_nop 0
	global_load_lds_dwordx4 v196, s[40:41]
	s_add_u32 m0, s32, 0x3000
	s_nop 0
	global_load_lds_dwordx4 v197, s[36:37]
	s_add_u32 m0, s32, 0xb000
	s_nop 0
	global_load_lds_dwordx4 v197, s[40:41]
.Lp1_notfirst:
	s_add_u32 s36, s36, 0x80
	s_addc_u32 s37, s37, 0
	s_add_u32 s40, s40, 0x80
	s_addc_u32 s41, s41, 0
	s_lshl_b32 s45, s86, 12
	s_add_u32 s46, s94, s45
	s_addc_u32 s47, s95, 0
	s_add_u32 s46, s46, 0x15000000
	s_addc_u32 s47, s47, 0
	s_lshl_b32 s45, s87, 12
	s_add_u32 s48, s94, s45
	s_addc_u32 s49, s95, 0
	s_add_u32 s48, s48, 0x19000000
	s_addc_u32 s49, s49, 0
	v_mov_b32_e32 v0, 0
	v_mov_b32_e32 v1, 0
	v_mov_b32_e32 v2, 0
	v_mov_b32_e32 v3, 0
	v_mov_b32_e32 v4, 0
	v_mov_b32_e32 v5, 0
	v_mov_b32_e32 v6, 0
	v_mov_b32_e32 v7, 0
	v_mov_b32_e32 v8, 0
	v_mov_b32_e32 v9, 0
	v_mov_b32_e32 v10, 0
	v_mov_b32_e32 v11, 0
	v_mov_b32_e32 v12, 0
	v_mov_b32_e32 v13, 0
	v_mov_b32_e32 v14, 0
	v_mov_b32_e32 v15, 0
	v_mov_b32_e32 v16, 0
	v_mov_b32_e32 v17, 0
	v_mov_b32_e32 v18, 0
	v_mov_b32_e32 v19, 0
	v_mov_b32_e32 v20, 0
	v_mov_b32_e32 v21, 0
	v_mov_b32_e32 v22, 0
	v_mov_b32_e32 v23, 0
	v_mov_b32_e32 v24, 0
	v_mov_b32_e32 v25, 0
	v_mov_b32_e32 v26, 0
	v_mov_b32_e32 v27, 0
	v_mov_b32_e32 v28, 0
	v_mov_b32_e32 v29, 0
	v_mov_b32_e32 v30, 0
	v_mov_b32_e32 v31, 0
	v_mov_b32_e32 v32, 0
	v_mov_b32_e32 v33, 0
	v_mov_b32_e32 v34, 0
	v_mov_b32_e32 v35, 0
	v_mov_b32_e32 v36, 0
	v_mov_b32_e32 v37, 0
	v_mov_b32_e32 v38, 0
	v_mov_b32_e32 v39, 0
	v_mov_b32_e32 v40, 0
	v_mov_b32_e32 v41, 0
	v_mov_b32_e32 v42, 0
	v_mov_b32_e32 v43, 0
	v_mov_b32_e32 v44, 0
	v_mov_b32_e32 v45, 0
	v_mov_b32_e32 v46, 0
	v_mov_b32_e32 v47, 0
	v_mov_b32_e32 v48, 0
	v_mov_b32_e32 v49, 0
	v_mov_b32_e32 v50, 0
	v_mov_b32_e32 v51, 0
	v_mov_b32_e32 v52, 0
	v_mov_b32_e32 v53, 0
	v_mov_b32_e32 v54, 0
	v_mov_b32_e32 v55, 0
	v_mov_b32_e32 v56, 0
	v_mov_b32_e32 v57, 0
	v_mov_b32_e32 v58, 0
	v_mov_b32_e32 v59, 0
	v_mov_b32_e32 v60, 0
	v_mov_b32_e32 v61, 0
	v_mov_b32_e32 v62, 0
	v_mov_b32_e32 v63, 0
	s_mov_b32 s44, 0
.Lp1_kloop:
	s_waitcnt vmcnt(0)
	s_barrier
	s_add_u32 m0, s32, 0x4000
	s_nop 0
	global_load_lds_dwordx4 v194, s[36:37]
	s_add_u32 m0, s32, 0xc000
	s_nop 0
	global_load_lds_dwordx4 v194, s[40:41]
	s_add_u32 m0, s32, 0x5000
	s_nop 0
	global_load_lds_dwordx4 v195, s[36:37]
	s_add_u32 m0, s32, 0xd000
	s_nop 0
	global_load_lds_dwordx4 v195, s[40:41]
	s_add_u32 m0, s32, 0x6000
	s_nop 0
	global_load_lds_dwordx4 v196, s[36:37]
	s_add_u32 m0, s32, 0xe000
	s_nop 0
	global_load_lds_dwordx4 v196, s[40:41]
	s_add_u32 m0, s32, 0x7000
	s_nop 0
	global_load_lds_dwordx4 v197, s[36:37]
	s_add_u32 m0, s32, 0xf000
	s_nop 0
	global_load_lds_dwordx4 v197, s[40:41]
	s_add_u32 s36, s36, 0x80
	s_addc_u32 s37, s37, 0
	s_add_u32 s40, s40, 0x80
	s_addc_u32 s41, s41, 0
	ds_read_b128 v[146:149], v201 offset:0
	ds_read_b128 v[150:153], v201 offset:2048
	ds_read_b128 v[154:157], v201 offset:4096
	ds_read_b128 v[158:161], v201 offset:6144
	ds_read_b128 v[130:133], v198 offset:0
	ds_read_b128 v[134:137], v198 offset:2048
	ds_read_b128 v[138:141], v198 offset:4096
	ds_read_b128 v[142:145], v198 offset:6144
	ds_read_b128 v[178:181], v202 offset:0
	ds_read_b128 v[182:185], v202 offset:2048
	ds_read_b128 v[186:189], v202 offset:4096
	ds_read_b128 v[190:193], v202 offset:6144
	ds_read_b128 v[162:165], v200 offset:0
	ds_read_b128 v[166:169], v200 offset:2048
	ds_read_b128 v[170:173], v200 offset:4096
	ds_read_b128 v[174:177], v200 offset:6144
	s_setprio 1
	s_waitcnt lgkmcnt(8)
	v_mfma_f32_16x16x32_bf16 v[60:63], v[146:149], v[130:133], v[60:63]
	v_mfma_f32_16x16x32_bf16 v[56:59], v[150:153], v[130:133], v[56:59]
	v_mfma_f32_16x16x32_bf16 v[52:55], v[154:157], v[130:133], v[52:55]
	v_mfma_f32_16x16x32_bf16 v[48:51], v[158:161], v[130:133], v[48:51]
	v_mfma_f32_16x16x32_bf16 v[44:47], v[146:149], v[134:137], v[44:47]
	v_mfma_f32_16x16x32_bf16 v[40:43], v[150:153], v[134:137], v[40:43]
	v_mfma_f32_16x16x32_bf16 v[36:39], v[154:157], v[134:137], v[36:39]
	v_mfma_f32_16x16x32_bf16 v[32:35], v[158:161], v[134:137], v[32:35]
	v_mfma_f32_16x16x32_bf16 v[28:31], v[146:149], v[138:141], v[28:31]
	v_mfma_f32_16x16x32_bf16 v[24:27], v[150:153], v[138:141], v[24:27]
	v_mfma_f32_16x16x32_bf16 v[20:23], v[154:157], v[138:141], v[20:23]
	v_mfma_f32_16x16x32_bf16 v[16:19], v[158:161], v[138:141], v[16:19]
	v_mfma_f32_16x16x32_bf16 v[12:15], v[146:149], v[142:145], v[12:15]
	v_mfma_f32_16x16x32_bf16 v[8:11], v[150:153], v[142:145], v[8:11]
	v_mfma_f32_16x16x32_bf16 v[4:7], v[154:157], v[142:145], v[4:7]
	v_mfma_f32_16x16x32_bf16 v[0:3], v[158:161], v[142:145], v[0:3]
	s_waitcnt lgkmcnt(0)
	v_mfma_f32_16x16x32_bf16 v[60:63], v[178:181], v[162:165], v[60:63]
	v_mfma_f32_16x16x32_bf16 v[56:59], v[182:185], v[162:165], v[56:59]
	v_mfma_f32_16x16x32_bf16 v[52:55], v[186:189], v[162:165], v[52:55]
	v_mfma_f32_16x16x32_bf16 v[48:51], v[190:193], v[162:165], v[48:51]
	v_mfma_f32_16x16x32_bf16 v[44:47], v[178:181], v[166:169], v[44:47]
	v_mfma_f32_16x16x32_bf16 v[40:43], v[182:185], v[166:169], v[40:43]
	v_mfma_f32_16x16x32_bf16 v[36:39], v[186:189], v[166:169], v[36:39]
	v_mfma_f32_16x16x32_bf16 v[32:35], v[190:193], v[166:169], v[32:35]
	v_mfma_f32_16x16x32_bf16 v[28:31], v[178:181], v[170:173], v[28:31]
	v_mfma_f32_16x16x32_bf16 v[24:27], v[182:185], v[170:173], v[24:27]
	v_mfma_f32_16x16x32_bf16 v[20:23], v[186:189], v[170:173], v[20:23]
	v_mfma_f32_16x16x32_bf16 v[16:19], v[190:193], v[170:173], v[16:19]
	v_mfma_f32_16x16x32_bf16 v[12:15], v[178:181], v[174:177], v[12:15]
	v_mfma_f32_16x16x32_bf16 v[8:11], v[182:185], v[174:177], v[8:11]
	v_mfma_f32_16x16x32_bf16 v[4:7], v[186:189], v[174:177], v[4:7]
	v_mfma_f32_16x16x32_bf16 v[0:3], v[190:193], v[174:177], v[0:3]
	s_setprio 0
	s_waitcnt vmcnt(0)
	s_barrier
	s_add_u32 m0, s32, 0x0
	s_nop 0
	global_load_lds_dwordx4 v194, s[36:37]
	s_add_u32 m0, s32, 0x8000
	s_nop 0
	global_load_lds_dwordx4 v194, s[40:41]
	s_add_u32 m0, s32, 0x1000
	s_nop 0
	global_load_lds_dwordx4 v195, s[36:37]
	s_add_u32 m0, s32, 0x9000
	s_nop 0
	global_load_lds_dwordx4 v195, s[40:41]
	s_add_u32 m0, s32, 0x2000
	s_nop 0
	global_load_lds_dwordx4 v196, s[36:37]
	s_add_u32 m0, s32, 0xa000
	s_nop 0
	global_load_lds_dwordx4 v196, s[40:41]
	s_add_u32 m0, s32, 0x3000
	s_nop 0
	global_load_lds_dwordx4 v197, s[36:37]
	s_add_u32 m0, s32, 0xb000
	s_nop 0
	global_load_lds_dwordx4 v197, s[40:41]
	s_add_u32 s36, s36, 0x80
	s_addc_u32 s37, s37, 0
	s_add_u32 s40, s40, 0x80
	s_addc_u32 s41, s41, 0
	ds_read_b128 v[146:149], v201 offset:16384
	ds_read_b128 v[150:153], v201 offset:18432
	ds_read_b128 v[154:157], v201 offset:20480
	ds_read_b128 v[158:161], v201 offset:22528
	ds_read_b128 v[130:133], v198 offset:16384
	ds_read_b128 v[134:137], v198 offset:18432
	ds_read_b128 v[138:141], v198 offset:20480
	ds_read_b128 v[142:145], v198 offset:22528
	ds_read_b128 v[178:181], v202 offset:16384
	ds_read_b128 v[182:185], v202 offset:18432
	ds_read_b128 v[186:189], v202 offset:20480
	ds_read_b128 v[190:193], v202 offset:22528
	ds_read_b128 v[162:165], v200 offset:16384
	ds_read_b128 v[166:169], v200 offset:18432
	ds_read_b128 v[170:173], v200 offset:20480
	ds_read_b128 v[174:177], v200 offset:22528
	s_setprio 1
	s_waitcnt lgkmcnt(8)
	v_mfma_f32_16x16x32_bf16 v[60:63], v[146:149], v[130:133], v[60:63]
	v_mfma_f32_16x16x32_bf16 v[56:59], v[150:153], v[130:133], v[56:59]
	v_mfma_f32_16x16x32_bf16 v[52:55], v[154:157], v[130:133], v[52:55]
	v_mfma_f32_16x16x32_bf16 v[48:51], v[158:161], v[130:133], v[48:51]
	v_mfma_f32_16x16x32_bf16 v[44:47], v[146:149], v[134:137], v[44:47]
	v_mfma_f32_16x16x32_bf16 v[40:43], v[150:153], v[134:137], v[40:43]
	v_mfma_f32_16x16x32_bf16 v[36:39], v[154:157], v[134:137], v[36:39]
	v_mfma_f32_16x16x32_bf16 v[32:35], v[158:161], v[134:137], v[32:35]
	v_mfma_f32_16x16x32_bf16 v[28:31], v[146:149], v[138:141], v[28:31]
	v_mfma_f32_16x16x32_bf16 v[24:27], v[150:153], v[138:141], v[24:27]
	v_mfma_f32_16x16x32_bf16 v[20:23], v[154:157], v[138:141], v[20:23]
	v_mfma_f32_16x16x32_bf16 v[16:19], v[158:161], v[138:141], v[16:19]
	v_mfma_f32_16x16x32_bf16 v[12:15], v[146:149], v[142:145], v[12:15]
	v_mfma_f32_16x16x32_bf16 v[8:11], v[150:153], v[142:145], v[8:11]
	v_mfma_f32_16x16x32_bf16 v[4:7], v[154:157], v[142:145], v[4:7]
	v_mfma_f32_16x16x32_bf16 v[0:3], v[158:161], v[142:145], v[0:3]
	s_waitcnt lgkmcnt(0)
	v_mfma_f32_16x16x32_bf16 v[60:63], v[178:181], v[162:165], v[60:63]
	v_mfma_f32_16x16x32_bf16 v[56:59], v[182:185], v[162:165], v[56:59]
	v_mfma_f32_16x16x32_bf16 v[52:55], v[186:189], v[162:165], v[52:55]
	v_mfma_f32_16x16x32_bf16 v[48:51], v[190:193], v[162:165], v[48:51]
	v_mfma_f32_16x16x32_bf16 v[44:47], v[178:181], v[166:169], v[44:47]
	v_mfma_f32_16x16x32_bf16 v[40:43], v[182:185], v[166:169], v[40:43]
	v_mfma_f32_16x16x32_bf16 v[36:39], v[186:189], v[166:169], v[36:39]
	v_mfma_f32_16x16x32_bf16 v[32:35], v[190:193], v[166:169], v[32:35]
	v_mfma_f32_16x16x32_bf16 v[28:31], v[178:181], v[170:173], v[28:31]
	v_mfma_f32_16x16x32_bf16 v[24:27], v[182:185], v[170:173], v[24:27]
	v_mfma_f32_16x16x32_bf16 v[20:23], v[186:189], v[170:173], v[20:23]
	v_mfma_f32_16x16x32_bf16 v[16:19], v[190:193], v[170:173], v[16:19]
	v_mfma_f32_16x16x32_bf16 v[12:15], v[178:181], v[174:177], v[12:15]
	v_mfma_f32_16x16x32_bf16 v[8:11], v[182:185], v[174:177], v[8:11]
	v_mfma_f32_16x16x32_bf16 v[4:7], v[186:189], v[174:177], v[4:7]
	v_mfma_f32_16x16x32_bf16 v[0:3], v[190:193], v[174:177], v[0:3]
	s_setprio 0
	s_add_i32 s44, s44, 1
	s_cmp_lt_u32 s44, 15
	s_cbranch_scc1 .Lp1_kloop
	s_waitcnt vmcnt(0)
	s_barrier
	s_add_u32 m0, s32, 0x4000
	s_nop 0
	global_load_lds_dwordx4 v194, s[36:37]
	s_add_u32 m0, s32, 0xc000
	s_nop 0
	global_load_lds_dwordx4 v194, s[40:41]
	s_add_u32 m0, s32, 0x5000
	s_nop 0
	global_load_lds_dwordx4 v195, s[36:37]
	s_add_u32 m0, s32, 0xd000
	s_nop 0
	global_load_lds_dwordx4 v195, s[40:41]
	s_add_u32 m0, s32, 0x6000
	s_nop 0
	global_load_lds_dwordx4 v196, s[36:37]
	s_add_u32 m0, s32, 0xe000
	s_nop 0
	global_load_lds_dwordx4 v196, s[40:41]
	s_add_u32 m0, s32, 0x7000
	s_nop 0
	global_load_lds_dwordx4 v197, s[36:37]
	s_add_u32 m0, s32, 0xf000
	s_nop 0
	global_load_lds_dwordx4 v197, s[40:41]
	s_add_u32 s36, s36, 0x80
	s_addc_u32 s37, s37, 0
	s_add_u32 s40, s40, 0x80
	s_addc_u32 s41, s41, 0
	ds_read_b128 v[146:149], v201 offset:0
	ds_read_b128 v[150:153], v201 offset:2048
	ds_read_b128 v[154:157], v201 offset:4096
	ds_read_b128 v[158:161], v201 offset:6144
	ds_read_b128 v[130:133], v198 offset:0
	ds_read_b128 v[134:137], v198 offset:2048
	ds_read_b128 v[138:141], v198 offset:4096
	ds_read_b128 v[142:145], v198 offset:6144
	ds_read_b128 v[178:181], v202 offset:0
	ds_read_b128 v[182:185], v202 offset:2048
	ds_read_b128 v[186:189], v202 offset:4096
	ds_read_b128 v[190:193], v202 offset:6144
	ds_read_b128 v[162:165], v200 offset:0
	ds_read_b128 v[166:169], v200 offset:2048
	ds_read_b128 v[170:173], v200 offset:4096
	ds_read_b128 v[174:177], v200 offset:6144
	s_setprio 1
	s_waitcnt lgkmcnt(8)
	v_mfma_f32_16x16x32_bf16 v[60:63], v[146:149], v[130:133], v[60:63]
	v_mfma_f32_16x16x32_bf16 v[56:59], v[150:153], v[130:133], v[56:59]
	v_mfma_f32_16x16x32_bf16 v[52:55], v[154:157], v[130:133], v[52:55]
	v_mfma_f32_16x16x32_bf16 v[48:51], v[158:161], v[130:133], v[48:51]
	v_mfma_f32_16x16x32_bf16 v[44:47], v[146:149], v[134:137], v[44:47]
	v_mfma_f32_16x16x32_bf16 v[40:43], v[150:153], v[134:137], v[40:43]
	v_mfma_f32_16x16x32_bf16 v[36:39], v[154:157], v[134:137], v[36:39]
	v_mfma_f32_16x16x32_bf16 v[32:35], v[158:161], v[134:137], v[32:35]
	v_mfma_f32_16x16x32_bf16 v[28:31], v[146:149], v[138:141], v[28:31]
	v_mfma_f32_16x16x32_bf16 v[24:27], v[150:153], v[138:141], v[24:27]
	v_mfma_f32_16x16x32_bf16 v[20:23], v[154:157], v[138:141], v[20:23]
	v_mfma_f32_16x16x32_bf16 v[16:19], v[158:161], v[138:141], v[16:19]
	v_mfma_f32_16x16x32_bf16 v[12:15], v[146:149], v[142:145], v[12:15]
	v_mfma_f32_16x16x32_bf16 v[8:11], v[150:153], v[142:145], v[8:11]
	v_mfma_f32_16x16x32_bf16 v[4:7], v[154:157], v[142:145], v[4:7]
	v_mfma_f32_16x16x32_bf16 v[0:3], v[158:161], v[142:145], v[0:3]
	s_waitcnt lgkmcnt(0)
	v_mfma_f32_16x16x32_bf16 v[60:63], v[178:181], v[162:165], v[60:63]
	v_mfma_f32_16x16x32_bf16 v[56:59], v[182:185], v[162:165], v[56:59]
	v_mfma_f32_16x16x32_bf16 v[52:55], v[186:189], v[162:165], v[52:55]
	v_mfma_f32_16x16x32_bf16 v[48:51], v[190:193], v[162:165], v[48:51]
	v_mfma_f32_16x16x32_bf16 v[44:47], v[178:181], v[166:169], v[44:47]
	v_mfma_f32_16x16x32_bf16 v[40:43], v[182:185], v[166:169], v[40:43]
	v_mfma_f32_16x16x32_bf16 v[36:39], v[186:189], v[166:169], v[36:39]
	v_mfma_f32_16x16x32_bf16 v[32:35], v[190:193], v[166:169], v[32:35]
	v_mfma_f32_16x16x32_bf16 v[28:31], v[178:181], v[170:173], v[28:31]
	v_mfma_f32_16x16x32_bf16 v[24:27], v[182:185], v[170:173], v[24:27]
	v_mfma_f32_16x16x32_bf16 v[20:23], v[186:189], v[170:173], v[20:23]
	v_mfma_f32_16x16x32_bf16 v[16:19], v[190:193], v[170:173], v[16:19]
	v_mfma_f32_16x16x32_bf16 v[12:15], v[178:181], v[174:177], v[12:15]
	v_mfma_f32_16x16x32_bf16 v[8:11], v[182:185], v[174:177], v[8:11]
	v_mfma_f32_16x16x32_bf16 v[4:7], v[186:189], v[174:177], v[4:7]
	v_mfma_f32_16x16x32_bf16 v[0:3], v[190:193], v[174:177], v[0:3]
	s_setprio 0
	s_waitcnt vmcnt(0)
	s_barrier
	s_and_b64 vcc, exec, s[4:5]
	s_cbranch_vccz .Lp1_nonext
	s_add_u32 m0, s32, 0x0
	s_nop 0
	global_load_lds_dwordx4 v194, s[46:47]
	s_add_u32 m0, s32, 0x8000
	s_nop 0
	global_load_lds_dwordx4 v194, s[48:49]
	s_add_u32 m0, s32, 0x1000
	s_nop 0
	global_load_lds_dwordx4 v195, s[46:47]
	s_add_u32 m0, s32, 0x9000
	s_nop 0
	global_load_lds_dwordx4 v195, s[48:49]
	s_add_u32 m0, s32, 0x2000
	s_nop 0
	global_load_lds_dwordx4 v196, s[46:47]
	s_add_u32 m0, s32, 0xa000
	s_nop 0
	global_load_lds_dwordx4 v196, s[48:49]
	s_add_u32 m0, s32, 0x3000
	s_nop 0
	global_load_lds_dwordx4 v197, s[46:47]
	s_add_u32 m0, s32, 0xb000
	s_nop 0
	global_load_lds_dwordx4 v197, s[48:49]
.Lp1_nonext:
	ds_read_b128 v[146:149], v201 offset:16384
	ds_read_b128 v[150:153], v201 offset:18432
	ds_read_b128 v[154:157], v201 offset:20480
	ds_read_b128 v[158:161], v201 offset:22528
	ds_read_b128 v[130:133], v198 offset:16384
	ds_read_b128 v[134:137], v198 offset:18432
	ds_read_b128 v[138:141], v198 offset:20480
	ds_read_b128 v[142:145], v198 offset:22528
	ds_read_b128 v[178:181], v202 offset:16384
	ds_read_b128 v[182:185], v202 offset:18432
	ds_read_b128 v[186:189], v202 offset:20480
	ds_read_b128 v[190:193], v202 offset:22528
	ds_read_b128 v[162:165], v200 offset:16384
	ds_read_b128 v[166:169], v200 offset:18432
	ds_read_b128 v[170:173], v200 offset:20480
	ds_read_b128 v[174:177], v200 offset:22528
	s_setprio 1
	s_waitcnt lgkmcnt(8)
	v_mfma_f32_16x16x32_bf16 v[60:63], v[146:149], v[130:133], v[60:63]
	v_mfma_f32_16x16x32_bf16 v[56:59], v[150:153], v[130:133], v[56:59]
	v_mfma_f32_16x16x32_bf16 v[52:55], v[154:157], v[130:133], v[52:55]
	v_mfma_f32_16x16x32_bf16 v[48:51], v[158:161], v[130:133], v[48:51]
	v_mfma_f32_16x16x32_bf16 v[44:47], v[146:149], v[134:137], v[44:47]
	v_mfma_f32_16x16x32_bf16 v[40:43], v[150:153], v[134:137], v[40:43]
	v_mfma_f32_16x16x32_bf16 v[36:39], v[154:157], v[134:137], v[36:39]
	v_mfma_f32_16x16x32_bf16 v[32:35], v[158:161], v[134:137], v[32:35]
	v_mfma_f32_16x16x32_bf16 v[28:31], v[146:149], v[138:141], v[28:31]
	v_mfma_f32_16x16x32_bf16 v[24:27], v[150:153], v[138:141], v[24:27]
	v_mfma_f32_16x16x32_bf16 v[20:23], v[154:157], v[138:141], v[20:23]
	v_mfma_f32_16x16x32_bf16 v[16:19], v[158:161], v[138:141], v[16:19]
	v_mfma_f32_16x16x32_bf16 v[12:15], v[146:149], v[142:145], v[12:15]
	v_mfma_f32_16x16x32_bf16 v[8:11], v[150:153], v[142:145], v[8:11]
	v_mfma_f32_16x16x32_bf16 v[4:7], v[154:157], v[142:145], v[4:7]
	v_mfma_f32_16x16x32_bf16 v[0:3], v[158:161], v[142:145], v[0:3]
	s_waitcnt lgkmcnt(0)
	v_mfma_f32_16x16x32_bf16 v[60:63], v[178:181], v[162:165], v[60:63]
	v_mfma_f32_16x16x32_bf16 v[56:59], v[182:185], v[162:165], v[56:59]
	v_mfma_f32_16x16x32_bf16 v[52:55], v[186:189], v[162:165], v[52:55]
	v_mfma_f32_16x16x32_bf16 v[48:51], v[190:193], v[162:165], v[48:51]
	v_mfma_f32_16x16x32_bf16 v[44:47], v[178:181], v[166:169], v[44:47]
	v_mfma_f32_16x16x32_bf16 v[40:43], v[182:185], v[166:169], v[40:43]
	v_mfma_f32_16x16x32_bf16 v[36:39], v[186:189], v[166:169], v[36:39]
	v_mfma_f32_16x16x32_bf16 v[32:35], v[190:193], v[166:169], v[32:35]
	v_mfma_f32_16x16x32_bf16 v[28:31], v[178:181], v[170:173], v[28:31]
	v_mfma_f32_16x16x32_bf16 v[24:27], v[182:185], v[170:173], v[24:27]
	v_mfma_f32_16x16x32_bf16 v[20:23], v[186:189], v[170:173], v[20:23]
	v_mfma_f32_16x16x32_bf16 v[16:19], v[190:193], v[170:173], v[16:19]
	v_mfma_f32_16x16x32_bf16 v[12:15], v[178:181], v[174:177], v[12:15]
	v_mfma_f32_16x16x32_bf16 v[8:11], v[182:185], v[174:177], v[8:11]
	v_mfma_f32_16x16x32_bf16 v[4:7], v[186:189], v[174:177], v[4:7]
	v_mfma_f32_16x16x32_bf16 v[0:3], v[190:193], v[174:177], v[0:3]
	s_setprio 0
	v_add_u32_e32 v88, s8, v99
	v_ashrrev_i32_e32 v89, 31, v88
	v_readlane_b32 s4, v242, 52
	v_lshlrev_b64 v[86:87], 13, v[88:89]
	v_readlane_b32 s5, v242, 53
	v_or_b32_e32 v64, s81, v100
	s_nop 0
	v_lshl_add_u64 v[92:93], s[4:5], 0, v[86:87]
	v_mov_b64_e32 v[86:87], s[28:29]
	v_mad_i64_i32 v[90:91], s[4:5], v88, s25, v[86:87]
	v_cmp_lt_i32_e64 s[4:5], s59, v64
	s_and_saveexec_b64 s[6:7], s[4:5]
	s_xor_b64 s[6:7], exec, s[6:7]
	s_cbranch_execz .LBB0_134
	s_cmpk_gt_u32 s81, 0x19ff
	s_mov_b64 s[8:9], -1
	s_cbranch_scc0 .LBB0_132
	v_lshl_add_u64 v[86:87], v[64:65], 1, v[92:93]
	v_lshl_add_u64 v[96:97], v[86:87], 0, s[18:19]
	s_mov_b64 s[8:9], 0

.LBB0_313:
	s_or_b64 exec, exec, s[0:1]
	s_mov_b64 s[4:5], exec
	v_mov_b32_e32 v9, v8
	s_mov_b32 s13, 0xa0000
	s_mov_b32 s14, 0xcccccccd
	s_mov_b32 s15, 0x3cf5c28f
	s_mov_b32 s18, 0xbeaaaaab
.Lp2l_loop:
	v_cmp_gt_u32_e32 vcc, s13, v9
	s_and_b64 exec, exec, vcc
	s_cbranch_execz .Lp2l_done
	v_mul_hi_u32 v10, v9, s14
	v_lshrrev_b32_e32 v10, 5, v10
	v_mul_u32_u24_e32 v11, 40, v10
	v_sub_u32_e32 v11, v9, v11
	v_mul_u32_u24_e32 v12, 0x1b00, v10
	v_lshl_add_u32 v12, v11, 4, v12
	v_add_u32_e32 v12, 0x1800, v12
	v_and_b32_e32 v14, 0xfff, v10
	v_cmp_ne_u32_e64 s[6:7], 0, v14
	v_subrev_u32_e32 v14, 0x1b00, v12
	s_nop 1
	v_cndmask_b32_e64 v14, v12, v14, s[6:7]
	v_lshlrev_b32_e32 v15, 5, v11
	v_add_u32_e32 v15, 0x3000, v15
	v_cmp_gt_u32_e64 s[8:9], 36, v11
	v_cmp_gt_u32_e64 s[10:11], 8, v11
	v_cmp_gt_u32_e64 s[16:17], 16, v11
	v_lshlrev_b32_e32 v13, 7, v10
	v_lshl_add_u32 v13, v11, 4, v13
	v_add_u32_e32 v13, 0x1b000000, v13
	v_add_u32_e32 v48, 0x1fff80, v13
	v_cndmask_b32_e64 v13, v48, v13, s[10:11]
	v_mul_u32_u24_e32 v48, 0x180, v10
	v_lshl_add_u32 v48, v11, 4, v48
	v_add_u32_e32 v48, 0x1b3fff00, v48
	v_cndmask_b32_e64 v13, v48, v13, s[16:17]
	v_mov_b32_e32 v56, 0xbfb8aa3b
	v_mov_b32_e32 v49, 0xc038aa3b
	v_cndmask_b32_e64 v56, v56, v49, s[10:11]
	s_mov_b64 s[20:21], exec
	s_and_b64 exec, exec, s[8:9]
	global_load_dwordx4 v[16:19], v12, s[94:95]
	global_load_dwordx4 v[20:23], v14, s[94:95]
	global_load_dwordx4 v[24:27], v15, s[82:83]
	global_load_dwordx4 v[28:31], v15, s[82:83] offset:16
	s_mov_b64 exec, s[20:21]
	s_waitcnt vmcnt(0)
	v_cndmask_b32_e64 v20, 0, v20, s[6:7]
	v_cndmask_b32_e64 v21, 0, v21, s[6:7]
	v_cndmask_b32_e64 v22, 0, v22, s[6:7]
	v_cndmask_b32_e64 v23, 0, v23, s[6:7]
	v_lshlrev_b32_e32 v32, 16, v16
	v_lshlrev_b32_e32 v48, 16, v20
	v_and_b32_e32 v33, 0xffff0000, v16
	v_and_b32_e32 v49, 0xffff0000, v20
	v_lshlrev_b32_e32 v34, 16, v17
	v_lshlrev_b32_e32 v50, 16, v21
	v_and_b32_e32 v35, 0xffff0000, v17
	v_and_b32_e32 v51, 0xffff0000, v21
	v_lshlrev_b32_e32 v36, 16, v18
	v_lshlrev_b32_e32 v52, 16, v22
	v_and_b32_e32 v37, 0xffff0000, v18
	v_and_b32_e32 v53, 0xffff0000, v22
	v_lshlrev_b32_e32 v38, 16, v19
	v_lshlrev_b32_e32 v54, 16, v23
	v_and_b32_e32 v39, 0xffff0000, v19
	v_and_b32_e32 v55, 0xffff0000, v23
	v_sub_f32_e32 v48, v48, v32
	v_sub_f32_e32 v49, v49, v33
	v_sub_f32_e32 v50, v50, v34
	v_sub_f32_e32 v51, v51, v35
	v_sub_f32_e32 v52, v52, v36
	v_sub_f32_e32 v53, v53, v37
	v_sub_f32_e32 v54, v54, v38
	v_sub_f32_e32 v55, v55, v39
	v_fmac_f32_e32 v32, v24, v48
	v_fmac_f32_e32 v33, v25, v49
	v_fmac_f32_e32 v34, v26, v50
	v_fmac_f32_e32 v35, v27, v51
	v_fmac_f32_e32 v36, v28, v52
	v_fmac_f32_e32 v37, v29, v53
	v_fmac_f32_e32 v38, v30, v54
	v_fmac_f32_e32 v39, v31, v55
	v_mul_f32_e32 v40, v56, v32
	v_mul_f32_e32 v41, v56, v33
	v_mul_f32_e32 v42, v56, v34
	v_mul_f32_e32 v43, v56, v35
	v_mul_f32_e32 v44, v56, v36
	v_mul_f32_e32 v45, v56, v37
	v_mul_f32_e32 v46, v56, v38
	v_mul_f32_e32 v47, v56, v39
	v_exp_f32_e32 v40, v40
	v_exp_f32_e32 v41, v41
	v_exp_f32_e32 v42, v42
	v_exp_f32_e32 v43, v43
	v_exp_f32_e32 v44, v44
	v_exp_f32_e32 v45, v45
	v_exp_f32_e32 v46, v46
	v_exp_f32_e32 v47, v47
	v_add_f32_e32 v40, 1.0, v40
	v_add_f32_e32 v41, 1.0, v41
	v_add_f32_e32 v42, 1.0, v42
	v_add_f32_e32 v43, 1.0, v43
	v_add_f32_e32 v44, 1.0, v44
	v_add_f32_e32 v45, 1.0, v45
	v_add_f32_e32 v46, 1.0, v46
	v_add_f32_e32 v47, 1.0, v47
	v_rcp_f32_e32 v40, v40
	v_rcp_f32_e32 v41, v41
	v_rcp_f32_e32 v42, v42
	v_rcp_f32_e32 v43, v43
	v_rcp_f32_e32 v44, v44
	v_rcp_f32_e32 v45, v45
	v_rcp_f32_e32 v46, v46
	v_rcp_f32_e32 v47, v47
	v_mul_f32_e32 v48, v32, v32
	v_mul_f32_e32 v49, v33, v33
	v_mul_f32_e32 v50, v34, v34
	v_mul_f32_e32 v51, v35, v35
	v_mul_f32_e32 v52, v36, v36
	v_mul_f32_e32 v53, v37, v37
	v_mul_f32_e32 v54, v38, v38
	v_mul_f32_e32 v55, v39, v39
	v_fma_f32 v48, v48, s18, 1.0
	v_fma_f32 v49, v49, s18, 1.0
	v_fma_f32 v50, v50, s18, 1.0
	v_fma_f32 v51, v51, s18, 1.0
	v_fma_f32 v52, v52, s18, 1.0
	v_fma_f32 v53, v53, s18, 1.0
	v_fma_f32 v54, v54, s18, 1.0
	v_fma_f32 v55, v55, s18, 1.0
	v_mul_f32_e32 v48, v48, v32
	v_mul_f32_e32 v49, v49, v33
	v_mul_f32_e32 v50, v50, v34
	v_mul_f32_e32 v51, v51, v35
	v_mul_f32_e32 v52, v52, v36
	v_mul_f32_e32 v53, v53, v37
	v_mul_f32_e32 v54, v54, v38
	v_mul_f32_e32 v55, v55, v39
	v_fma_f32 v24, v40, 2.0, -1.0
	v_fma_f32 v25, v41, 2.0, -1.0
	v_fma_f32 v26, v42, 2.0, -1.0
	v_fma_f32 v27, v43, 2.0, -1.0
	v_fma_f32 v28, v44, 2.0, -1.0
	v_fma_f32 v29, v45, 2.0, -1.0
	v_fma_f32 v30, v46, 2.0, -1.0
	v_fma_f32 v31, v47, 2.0, -1.0
	v_cmp_lt_f32_e64 vcc, |v32|, s15
	s_nop 1
	v_cndmask_b32_e32 v24, v24, v48, vcc
	v_cmp_lt_f32_e64 vcc, |v33|, s15
	s_nop 1
	v_cndmask_b32_e32 v25, v25, v49, vcc
	v_cmp_lt_f32_e64 vcc, |v34|, s15
	s_nop 1
	v_cndmask_b32_e32 v26, v26, v50, vcc
	v_cmp_lt_f32_e64 vcc, |v35|, s15
	s_nop 1
	v_cndmask_b32_e32 v27, v27, v51, vcc
	v_cmp_lt_f32_e64 vcc, |v36|, s15
	s_nop 1
	v_cndmask_b32_e32 v28, v28, v52, vcc
	v_cmp_lt_f32_e64 vcc, |v37|, s15
	s_nop 1
	v_cndmask_b32_e32 v29, v29, v53, vcc
	v_cmp_lt_f32_e64 vcc, |v38|, s15
	s_nop 1
	v_cndmask_b32_e32 v30, v30, v54, vcc
	v_cmp_lt_f32_e64 vcc, |v39|, s15
	s_nop 1
	v_cndmask_b32_e32 v31, v31, v55, vcc
	v_cndmask_b32_e64 v40, v40, v32, s[16:17]
	v_cndmask_b32_e64 v41, v41, v33, s[16:17]
	v_cndmask_b32_e64 v42, v42, v34, s[16:17]
	v_cndmask_b32_e64 v43, v43, v35, s[16:17]
	v_cndmask_b32_e64 v44, v44, v36, s[16:17]
	v_cndmask_b32_e64 v45, v45, v37, s[16:17]
	v_cndmask_b32_e64 v46, v46, v38, s[16:17]
	v_cndmask_b32_e64 v47, v47, v39, s[16:17]
	v_cndmask_b32_e64 v40, v40, v24, s[10:11]
	v_cndmask_b32_e64 v41, v41, v25, s[10:11]
	v_cndmask_b32_e64 v42, v42, v26, s[10:11]
	v_cndmask_b32_e64 v43, v43, v27, s[10:11]
	v_cndmask_b32_e64 v44, v44, v28, s[10:11]
	v_cndmask_b32_e64 v45, v45, v29, s[10:11]
	v_cndmask_b32_e64 v46, v46, v30, s[10:11]
	v_cndmask_b32_e64 v47, v47, v31, s[10:11]
	v_cvt_pk_bf16_f32 v60, v40, v41
	v_cvt_pk_bf16_f32 v61, v42, v43
	v_cvt_pk_bf16_f32 v62, v44, v45
	v_cvt_pk_bf16_f32 v63, v46, v47
	v_cndmask_b32_e64 v60, 0, v60, s[8:9]
	v_cndmask_b32_e64 v61, 0, v61, s[8:9]
	v_cndmask_b32_e64 v62, 0, v62, s[8:9]
	v_cndmask_b32_e64 v63, 0, v63, s[8:9]
	global_store_dwordx4 v13, v[60:63], s[94:95]
	v_add_u32_e32 v9, s12, v9
	s_branch .Lp2l_loop
.Lp2l_done:
	s_mov_b64 exec, s[4:5]
	s_add_u32 s2, s94, 0x1b000000
	s_addc_u32 s3, s95, 0
	s_add_u32 s14, s94, 0x1b400000
	s_addc_u32 s15, s95, 0
